# attn QK K-frag prefetch 4-deep + V tile LDS key-permute for b128 reads + GU gemm loop global_load_lds saddr form (no VALU address math)
# speedup vs baseline: 1.0047x; 1.0047x over previous
; #define LAS __attribute__((address_space(3)))
; __device__ __forceinline__ int otid() { int t = threadIdx.x; asm volatile("" : "+v"(t)); return t; }
; __device__ __forceinline__ int obid() { int t = blockIdx.x; asm volatile("" : "+s"(t)); return t; }
; __device__ __forceinline__ void phase_attn(const Params& p, int S, int lgS, int B, int* counter, LAS unsigned char* lds) {
;     ...
;     const int tid = otid(), lane = tid & 63, wid = __builtin_amdgcn_readfirstlane(tid >> 6), r32 = lane & 31, hi = lane >> 5;
;     const bf16_t* Z = (const bf16_t*)(ws_ + WS_BIG + BG_Z); const bf16_t* VT = (const bf16_t*)(ws_ + WS_BIG + BG_VT); bf16_t* YC = (bf16_t*)(ws_ + WS_YC);
;     constexpr int KB = 128 * 72 * 2, BUFB = KB + 64 * 136 * 2;
;     const int nqt = S >> 8, lgq = lgS - 8, nunits = B * 8 * nqt, NT = S >> 7;
;     LAS float* wsf = (LAS float*)(lds + 2 * BUFB + wid * 256);
;     const int skey = tid >> 3, spc = tid & 7;
;     const int kdst = (skey * 72 + spc * 8) * 2, vdst = KB + (skey * 136 + spc * 8) * 2;
;     const int klane = (r32 * 72 + 8 * hi) * 2, vlane = (r32 * 136 + 4 * hi) * 2;
;     const int G_ = (int)gridDim.x, bid_ = obid(), nscan = B * 16, per = nunits / G_;
;     const bool deal = (nunits % G_ == 0) && (2 * nscan <= G_) && (per >= 2);
;     const int nmine = !deal ? ((bid_ < nunits) ? (nunits - bid_ + G_ - 1) / G_ : 0) : (bid_ < nscan ? per - 1 : (bid_ < 2 * nscan ? per + 1 : per));
;     for (int ui = 0; ui < nmine; ++ui) {
;         const int unit = (deal && ui == per) ? (bid_ - nscan) + G_ * (per - 1) : bid_ + ui * G_;
;         const int hq4 = unit & 3, qt = (unit >> 2) & (nqt - 1), bk = unit >> (2 + lgq), kvh = bk & 1, b = bk >> 1, qh = kvh * 4 + hq4;
;         const size_t rowq = (size_t)b * S + qt * 256 + wid * 32 + r32;
;         bf16x8 qr[4];
; #pragma unroll
;         for (int d0 = 0; d0 < 4; ++d0) qr[d0] = *(const bf16x8*)(Z + rowq * 2048 + qh * 64 + d0 * 16 + hi * 8);
;         const bf16_t* ksrc = Z + ((size_t)b * S + skey) * 2048 + 512 + kvh * 64 + spc * 8;
;         const bf16_t* vsrc = VT + (((size_t)(b * 128 + kvh * 64 + skey)) << lgS) + spc * 8;
;         u32x4 kreg0 = *(const u32x4*)ksrc, kreg1 = *(const u32x4*)(ksrc + (size_t)64 * 2048), vreg0 = *(const u32x4*)vsrc, vreg1 = *(const u32x4*)(vsrc + 64);
.LBB0_725:
	s_cmp_lt_i32 s1, 1
	s_cbranch_scc1 .LBB0_741
	s_ashr_i32 s4, s2, 6
	s_add_u32 s8, s6, 0x13800000
	s_addc_u32 s9, s7, 0
	s_lshl_b32 s2, s4, 8
	s_add_i32 s2, s2, 0
	v_lshlrev_b32_e32 v2, 3, v0
	v_bfe_u32 v3, v0, 5, 1
	s_add_i32 s10, s2, 0x11800
	v_ashrrev_i32_e32 v146, 3, v0
	v_and_b32_e32 v2, 56, v2
	s_movk_i32 s2, 0x48
	v_mad_u64_u32 v[4:5], s[2:3], v146, s2, v[2:3]
	v_readlane_b32 s2, v251, 30
	v_readlane_b32 s3, v251, 31
	v_and_b32_e32 v144, 31, v0
	v_lshlrev_b32_e32 v5, 6, v146
	v_readlane_b32 s3, v251, 39
	v_lshlrev_b32_e32 v145, 1, v4
	v_lshlrev_b32_e32 v149, 4, v0
	v_and_b32_e32 v149, 0x60, v149
	v_lshlrev_b32_e32 v5, 3, v0
	v_and_b32_e32 v5, 8, v5
	v_add_u32_e32 v149, v149, v5
	v_mul_u32_u24_e32 v5, 0x110, v146
	v_add_u32_e32 v149, v149, v5
	v_add_u32_e32 v149, 0x4800, v149
	v_mul_u32_u24_e32 v4, 0x48, v144
	v_lshlrev_b32_e32 v148, 3, v3
	s_sub_i32 s2, s0, s2
	s_mul_i32 s3, s3, s92
	v_lshlrev_b32_e32 v200, 1, v2
	v_and_b32_e32 v1, 63, v0
	v_add_lshl_u32 v198, v148, v4, 1
	s_add_i32 s2, s2, s3
	s_lshl_b32 s3, s4, 5
	v_lshl_add_u64 v[4:5], s[6:7], 0, v[200:201]
	s_mov_b64 s[4:5], 0x27800000
	v_lshl_add_u64 v[150:151], v[4:5], 0, s[4:5]
	v_lshlrev_b32_e32 v4, 2, v1
	v_and_b32_e32 v0, 7, v0
	v_xor_b32_e32 v209, 0x80, v4
	v_cmp_gt_u32_e64 s[4:5], 32, v1
	v_lshlrev_b32_e32 v1, 4, v3
	v_lshlrev_b32_e32 v4, 12, v3
	v_lshlrev_b32_e32 v200, 4, v0
	v_mul_u32_u24_e32 v199, 0x110, v144
	v_lshl_add_u32 v219, v144, 2, s10
	v_add_u32_e32 v222, s10, v1
	v_add_u32_e32 v5, 0, v148
	v_or_b32_e32 v6, 0x400, v4
	v_or_b32_e32 v8, 0x800, v4
	v_or_b32_e32 v10, 0xc00, v4
	v_or_b32_e32 v12, 0x2000, v4
	v_or_b32_e32 v14, 0x2400, v4
	v_or_b32_e32 v16, 0x2800, v4
	v_or_b32_e32 v18, 0x2c00, v4
	v_or_b32_e32 v20, 0x4000, v4
	v_or_b32_e32 v22, 0x4400, v4
	v_or_b32_e32 v24, 0x4800, v4
	v_or_b32_e32 v26, 0x4c00, v4
	v_or_b32_e32 v28, 0x6000, v4
	v_or_b32_e32 v30, 0x6400, v4
	v_or_b32_e32 v32, 0x6800, v4
	v_or_b32_e32 v34, 0x6c00, v4
	v_lshl_add_u64 v[0:1], s[6:7], 0, v[200:201]
	s_mov_b64 s[10:11], 0x13940400
	s_ashr_i32 s14, s3, 31
	v_ashrrev_i32_e32 v147, 31, v146
	v_lshl_add_u64 v[152:153], v[0:1], 0, s[10:11]
	s_mov_b32 s15, 0
	v_lshl_add_u32 v223, v148, 1, v199
	v_lshlrev_b32_e32 v200, 1, v144
	v_lshlrev_b32_e32 v154, 1, v4
	v_lshlrev_b32_e32 v156, 1, v6
	v_lshlrev_b32_e32 v158, 1, v8
	v_lshlrev_b32_e32 v160, 1, v10
	v_lshlrev_b32_e32 v162, 1, v12
	v_lshlrev_b32_e32 v164, 1, v14
	v_lshlrev_b32_e32 v166, 1, v16
	v_lshlrev_b32_e32 v168, 1, v18
	v_lshlrev_b32_e32 v170, 1, v20
	v_lshlrev_b32_e32 v172, 1, v22
	v_lshlrev_b32_e32 v174, 1, v24
	v_lshlrev_b32_e32 v176, 1, v26
	v_lshlrev_b32_e32 v178, 1, v28
	v_lshlrev_b32_e32 v180, 1, v30
	v_lshlrev_b32_e32 v182, 1, v32
	v_lshlrev_b32_e32 v184, 1, v34
	v_lshlrev_b32_e32 v186, 1, v148
	v_lshlrev_b32_e32 v188, 1, v2
	s_branch .LBB0_728

; #define LAS __attribute__((address_space(3)))
; __device__ __forceinline__ void phase_attn(const Params& p, int S, int lgS, int B, int* counter, LAS unsigned char* lds) {
;     ...
;     for (int ui = 0; ui < nmine; ++ui) {
;         const int unit = (deal && ui == per) ? (bid_ - nscan) + G_ * (per - 1) : bid_ + ui * G_;
;         const int hq4 = unit & 3, qt = (unit >> 2) & (nqt - 1), bk = unit >> (2 + lgq), kvh = bk & 1, b = bk >> 1, qh = kvh * 4 + hq4;
;         const size_t rowq = (size_t)b * S + qt * 256 + wid * 32 + r32;
;         bf16x8 qr[4];
; #pragma unroll
;         for (int d0 = 0; d0 < 4; ++d0) qr[d0] = *(const bf16x8*)(Z + rowq * 2048 + qh * 64 + d0 * 16 + hi * 8);
;         const bf16_t* ksrc = Z + ((size_t)b * S + skey) * 2048 + 512 + kvh * 64 + spc * 8;
;         const bf16_t* vsrc = VT + (((size_t)(b * 128 + kvh * 64 + skey)) << lgS) + spc * 8;
;         u32x4 kreg0 = *(const u32x4*)ksrc, kreg1 = *(const u32x4*)(ksrc + (size_t)64 * 2048), vreg0 = *(const u32x4*)vsrc, vreg1 = *(const u32x4*)(vsrc + 64);
;         *(LAS u32x4*)(lds + kdst) = kreg0; *(LAS u32x4*)(lds + kdst + 64 * 144) = kreg1; *(LAS u32x4*)(lds + vdst) = vreg0; *(LAS u32x4*)(lds + vdst + 128) = vreg1;
;         __syncthreads();
;         float m_run = 0.f, l_run = 0.f;
;         f32x16 o0 = {0.f, 0.f, 0.f, 0.f, 0.f, 0.f, 0.f, 0.f, 0.f, 0.f, 0.f, 0.f, 0.f, 0.f, 0.f, 0.f}, o1 = o0; const f32x16 zero16 = o0; f32x16 negm = o0;
;         for (int t = 0; t < NT; ++t) {
;             const LAS unsigned char* kb = lds + (t & 1) * BUFB; const LAS unsigned char* vb = kb + KB;
;             if (t + 1 < NT) { const bf16_t* kn = ksrc + (size_t)(t + 1) * 128 * 2048; const bf16_t* vn_ = vsrc + (t + 1) * 128;
;                 kreg0 = *(const u32x4*)kn; kreg1 = *(const u32x4*)(kn + (size_t)64 * 2048); vreg0 = *(const u32x4*)vn_; vreg1 = *(const u32x4*)(vn_ + 64); }
;             f32x16 pp[4] = {negm, negm, negm, negm};
;             const LAS unsigned char* kl = kb + klane; const LAS unsigned char* vl = vb + vlane;
; #pragma unroll
;             for (int d0 = 0; d0 < 4; ++d0)
; #pragma unroll
;                 for (int j = 0; j < 4; ++j) { const bf16x8 a = *(const LAS bf16x8*)(kl + (32 * j * 72 + 16 * d0) * 2); pp[j] = __builtin_amdgcn_mfma_f32_32x32x16_bf16(a, qr[d0], pp[j], 0, 0, 0); }
;             float mxa = fmaxf(pp[0][0], pp[1][0]), mxb = fmaxf(pp[2][0], pp[3][0]);
; #pragma unroll
.LBB0_728:
	v_readlane_b32 s10, v251, 38
	s_cmp_eq_u32 s15, s10
	v_readlane_b32 s16, v251, 34
	s_cselect_b64 s[10:11], -1, 0
	v_readlane_b32 s17, v251, 35
	s_and_b64 s[10:11], s[16:17], s[10:11]
	s_mul_i32 s16, s15, s92
	s_add_i32 s16, s16, s0
	s_and_b64 s[10:11], s[10:11], exec
	s_cselect_b32 s16, s2, s16
	s_lshr_b32 s10, s16, 2
	v_readlane_b32 s11, v251, 18
	s_and_b32 s10, s10, s11
	v_readlane_b32 s11, v251, 13
	s_ashr_i32 s11, s16, s11
	s_ashr_i32 s18, s11, 1
	s_ashr_i32 s19, s18, 31
	s_and_b32 s17, s11, 1
	s_lshl_b64 s[20:21], s[18:19], s87
	s_lshl_b32 s10, s10, 8
	s_add_u32 s10, s10, s3
	s_addc_u32 s11, 0, s14
	s_add_u32 s10, s10, s20
	s_addc_u32 s11, s11, s21
	s_lshl_b32 s16, s16, 6
	v_mov_b32_e32 v1, s11
	v_or_b32_e32 v0, s10, v144
	s_lshl_b32 s19, s17, 8
	s_and_b32 s16, s16, 0xc0
	v_lshlrev_b64 v[0:1], 12, v[0:1]
	s_or_b32 s16, s19, s16
	v_lshl_add_u64 v[0:1], s[8:9], 0, v[0:1]
	s_lshl_b32 s96, s16, 1
	v_lshl_add_u64 v[16:17], v[0:1], 0, s[96:97]
	v_lshl_add_u64 v[0:1], s[20:21], 0, v[146:147]
	v_lshlrev_b64 v[64:65], 12, v[0:1]
	v_lshl_add_u64 v[0:1], s[8:9], 0, v[64:65]
	s_lshl_b32 s19, s17, 6
	s_lshl_b32 s96, s17, 7
	s_lshl_b32 s17, s18, 7
	v_lshl_add_u64 v[0:1], v[0:1], 0, s[96:97]
	v_mov_b32_e32 v189, v201
	s_or_b32 s17, s17, s19
	v_lshl_add_u64 v[66:67], v[0:1], 0, v[188:189]
	v_add_u32_e32 v0, s17, v146
	s_mov_b32 s17, 0x40000
	v_ashrrev_i32_e32 v1, 31, v0
	v_add_co_u32_e32 v4, vcc, s17, v66
	v_lshlrev_b64 v[0:1], s87, v[0:1]
	s_nop 0
	v_addc_co_u32_e32 v5, vcc, 0, v67, vcc
	v_lshl_add_u64 v[190:191], v[0:1], 1, v[150:151]
	global_load_dwordx4 v[0:3], v[66:67], off offset:1024
	s_nop 0
	global_load_dwordx4 v[4:7], v[4:5], off offset:1024
	s_nop 0
	global_load_dwordx4 v[8:11], v[190:191], off
	global_load_dwordx4 v[12:15], v[190:191], off offset:128
	v_mov_b32_e32 v187, v201
	v_lshl_add_u64 v[16:17], v[16:17], 0, v[186:187]
	global_load_dwordx4 v[112:115], v[16:17], off
	global_load_dwordx4 v[116:119], v[16:17], off offset:32
	global_load_dwordx4 v[120:123], v[16:17], off offset:64
	global_load_dwordx4 v[124:127], v[16:17], off offset:96
	v_add_u32_e32 v68, 0, v145
	v_add_u32_e32 v86, 0, v198
	v_add_u32_e32 v69, 0, v149
	s_mov_b32 s17, 0x80000
	v_add_u32_e32 v93, 0x4800, v223
	v_add_u32_e32 v96, 0x6800, v223
	v_or_b32_e32 v64, s96, v64
	s_mov_b32 s18, 1
	v_lshl_add_u64 v[192:193], v[152:153], 0, v[64:65]
	s_movk_i32 s96, 0x100
	s_waitcnt vmcnt(7)
	ds_write_b128 v68, v[0:3]
	s_waitcnt vmcnt(6)
	ds_write_b128 v68, v[4:7] offset:9216
	s_waitcnt vmcnt(5)
	ds_write2_b64 v69, v[8:9], v[10:11] offset1:2
	s_waitcnt vmcnt(4)
	ds_write2_b64 v69, v[12:13], v[14:15] offset0:16 offset1:18
	s_waitcnt lgkmcnt(0)
	s_barrier
	ds_read_b128 v[0:3], v86
	ds_read_b128 v[70:73], v86 offset:32
	s_waitcnt vmcnt(3) lgkmcnt(1)
	v_mfma_f32_32x32x16_bf16 v[0:15], v[0:3], v[112:115], 0
	ds_read_b128 v[16:19], v86 offset:4608
	ds_read_b128 v[74:77], v86 offset:4640
	ds_read_b128 v[32:35], v86 offset:9216
	ds_read_b128 v[78:81], v86 offset:9248
	ds_read_b128 v[48:51], v86 offset:13824
	ds_read_b128 v[82:85], v86 offset:13856
	s_waitcnt lgkmcnt(5)
	v_mfma_f32_32x32x16_bf16 v[16:31], v[16:19], v[112:115], 0
	s_waitcnt lgkmcnt(3)
	v_mfma_f32_32x32x16_bf16 v[32:47], v[32:35], v[112:115], 0
	s_waitcnt vmcnt(2)
	v_mfma_f32_32x32x16_bf16 v[0:15], v[70:73], v[116:119], v[0:15]
	s_waitcnt lgkmcnt(1)
	v_mfma_f32_32x32x16_bf16 v[48:63], v[48:51], v[112:115], 0
	v_mfma_f32_32x32x16_bf16 v[16:31], v[74:77], v[116:119], v[16:31]
	ds_read_b128 v[70:73], v86 offset:64
	ds_read_b128 v[74:77], v86 offset:96
	v_mfma_f32_32x32x16_bf16 v[32:47], v[78:81], v[116:119], v[32:47]
	s_waitcnt vmcnt(1) lgkmcnt(1)
	v_mfma_f32_32x32x16_bf16 v[0:15], v[70:73], v[120:123], v[0:15]
	ds_read_b128 v[70:73], v86 offset:4672
	ds_read_b128 v[78:81], v86 offset:4704
	v_mfma_f32_32x32x16_bf16 v[48:63], v[82:85], v[116:119], v[48:63]
	s_waitcnt lgkmcnt(1)
	v_mfma_f32_32x32x16_bf16 v[16:31], v[70:73], v[120:123], v[16:31]
	ds_read_b128 v[70:73], v86 offset:9280
	ds_read_b128 v[82:85], v86 offset:9312
	s_waitcnt lgkmcnt(1)
	v_mfma_f32_32x32x16_bf16 v[32:47], v[70:73], v[120:123], v[32:47]
	ds_read_b128 v[70:73], v86 offset:13888
	ds_read_b128 v[86:89], v86 offset:13920
	s_waitcnt lgkmcnt(1)
	v_mfma_f32_32x32x16_bf16 v[48:63], v[70:73], v[120:123], v[48:63]
	v_add_co_u32_e32 v70, vcc, s17, v66
	s_mov_b32 s17, 0xc0000
	s_nop 0
	v_addc_co_u32_e32 v71, vcc, 0, v67, vcc
	v_add_co_u32_e32 v66, vcc, s17, v66
	s_waitcnt vmcnt(0)
	v_mfma_f32_32x32x16_bf16 v[32:47], v[82:85], v[124:127], v[32:47]
	v_addc_co_u32_e32 v67, vcc, 0, v67, vcc
	global_load_dwordx4 v[128:131], v[70:71], off offset:1024
	global_load_dwordx4 v[132:135], v[66:67], off offset:1024
	global_load_dwordx4 v[136:139], v[190:191], off offset:256
	global_load_dwordx4 v[140:143], v[190:191], off offset:384
	s_nop 6
	v_max_f32_e32 v73, v32, v32
	s_waitcnt lgkmcnt(0)
	v_mfma_f32_32x32x16_bf16 v[48:63], v[86:89], v[124:127], v[48:63]
	v_mfma_f32_32x32x16_bf16 v[0:15], v[74:77], v[124:127], v[0:15]
	s_nop 10
	v_max_f32_e32 v72, v48, v48
	v_max_f32_e32 v72, v73, v72
	v_max3_f32 v72, v72, v33, v49
	v_max3_f32 v72, v72, v34, v50
	v_max3_f32 v72, v72, v35, v51
	v_max3_f32 v72, v72, v36, v52
	v_max3_f32 v72, v72, v37, v53
	v_mfma_f32_32x32x16_bf16 v[16:31], v[78:81], v[124:127], v[16:31]
	v_max3_f32 v72, v72, v38, v54
	v_max3_f32 v72, v72, v39, v55
	v_max3_f32 v72, v72, v40, v56
	v_max3_f32 v72, v72, v41, v57
	v_max3_f32 v72, v72, v42, v58
	v_max3_f32 v72, v72, v43, v59
	v_max3_f32 v72, v72, v44, v60
	s_nop 4
	v_max3_f32 v74, v0, v16, v1
	v_max3_f32 v73, v74, v17, v2
	v_max3_f32 v73, v73, v18, v3
	v_max3_f32 v73, v73, v19, v4
	v_max3_f32 v73, v73, v20, v5
	v_max3_f32 v73, v73, v21, v6
	v_max3_f32 v73, v73, v22, v7
	v_max3_f32 v73, v73, v23, v8
	v_max3_f32 v73, v73, v24, v9
	v_max3_f32 v73, v73, v25, v10
	v_max3_f32 v73, v73, v26, v11
	v_max3_f32 v73, v73, v27, v12
	v_max3_f32 v73, v73, v28, v13
	v_max3_f32 v72, v72, v45, v61
	v_max3_f32 v73, v73, v29, v14
	v_max3_f32 v72, v72, v46, v62
	v_max3_f32 v73, v73, v30, v15
	v_max3_f32 v72, v72, v47, v63
	v_max3_f32 v72, v73, v31, v72
	ds_bpermute_b32 v73, v209, v72
	s_waitcnt lgkmcnt(0)
; #define LAS __attribute__((address_space(3)))
; #define LDS_WAIT() asm volatile("s_waitcnt lgkmcnt(0)" ::: "memory")
; __device__ __forceinline__ void phase_attn(const Params& p, int S, int lgS, int B, int* counter, LAS unsigned char* lds) {
;     ...
;             const bool first = (t == 0);
;             if (first || __any(mx > 8.f)) {
;                 const float d = first ? mx : fmaxf(mx, 0.f);
;                 m_run += d;
; #pragma unroll
;                 for (int j = 0; j < 4; ++j)
; #pragma unroll
;                     for (int r = 0; r < 16; ++r) pp[j][r] -= d;
; #pragma unroll
;                 for (int r = 0; r < 16; ++r) negm[r] = -m_run;
;                 if (!first) {
;                     const float alpha = __builtin_amdgcn_exp2f(-d); l_run *= alpha;
;                     if (hi == 0) wsf[r32] = alpha;
;                     LDS_WAIT();
; #pragma unroll
;                     for (int r = 0; r < 16; ++r) { const float f = wsf[crow(r, hi)]; o0[r] *= f; o1[r] *= f; }
;                     LDS_WAIT();
;                 }
;             }
;             float ls = 0.f;
; #pragma unroll
;             for (int j = 0; j < 4; ++j)
; #pragma unroll
;                 for (int r = 0; r < 16; ++r) { pp[j][r] = __builtin_amdgcn_exp2f(pp[j][r]); ls += pp[j][r]; }
;             l_run += ls;
; #pragma unroll
;             for (int j = 0; j < 4; ++j)
; #pragma unroll
;                 for (int kk = 0; kk < 2; ++kk) {
;                     const int ks = 2 * j + kk;
;                     const bf16x8 pa = pack8(pp[j][8 * kk], pp[j][8 * kk + 1], pp[j][8 * kk + 2], pp[j][8 * kk + 3], pp[j][8 * kk + 4], pp[j][8 * kk + 5], pp[j][8 * kk + 6], pp[j][8 * kk + 7]);
;                     const u32x2 v0a = *(const LAS u32x2*)(vl + (16 * ks) * 2), v0b = *(const LAS u32x2*)(vl + (16 * ks + 8) * 2);
;                     const u32x2 v1a = *(const LAS u32x2*)(vl + (32 * 136 + 16 * ks) * 2), v1b = *(const LAS u32x2*)(vl + (32 * 136 + 16 * ks + 8) * 2);
;                     const u32x4 f0 = {v0a.x, v0a.y, v0b.x, v0b.y}, f1 = {v1a.x, v1a.y, v1b.x, v1b.y};
;                     o0 = __builtin_amdgcn_mfma_f32_32x32x16_bf16(pa, __builtin_bit_cast(bf16x8, f0), o0, 0, 0, 0);
;                     o1 = __builtin_amdgcn_mfma_f32_32x32x16_bf16(pa, __builtin_bit_cast(bf16x8, f1), o1, 0, 0, 0);
;                 }
	v_max_f32_e32 v66, v73, v73
	v_max_f32_e32 v66, v72, v66
	v_sub_f32_e32 v0, v0, v66
	v_sub_f32_e32 v1, v1, v66
	v_exp_f32_e32 v0, v0
	v_sub_f32_e32 v2, v2, v66
	v_exp_f32_e32 v1, v1
	v_sub_f32_e32 v3, v3, v66
	v_exp_f32_e32 v2, v2
	v_sub_f32_e32 v4, v4, v66
	v_exp_f32_e32 v3, v3
	v_sub_f32_e32 v67, v32, v66
	v_sub_f32_e32 v32, v18, v66
	v_sub_f32_e32 v5, v5, v66
	v_add_f32_e32 v18, 0, v0
	v_exp_f32_e32 v4, v4
	v_sub_f32_e32 v6, v6, v66
	v_add_f32_e32 v18, v1, v18
	v_exp_f32_e32 v5, v5
	v_sub_f32_e32 v7, v7, v66
	v_add_f32_e32 v18, v2, v18
	v_exp_f32_e32 v6, v6
	v_sub_f32_e32 v8, v8, v66
	v_add_f32_e32 v18, v3, v18
	v_exp_f32_e32 v7, v7
	v_sub_f32_e32 v73, v36, v66
	v_sub_f32_e32 v9, v9, v66
	v_add_f32_e32 v18, v4, v18
	v_exp_f32_e32 v36, v8
	v_sub_f32_e32 v74, v37, v66
	v_sub_f32_e32 v10, v10, v66
	v_add_f32_e32 v18, v5, v18
	v_exp_f32_e32 v37, v9
	v_sub_f32_e32 v75, v38, v66
	v_sub_f32_e32 v11, v11, v66
	v_add_f32_e32 v18, v6, v18
	v_exp_f32_e32 v38, v10
	v_sub_f32_e32 v76, v39, v66
	v_sub_f32_e32 v12, v12, v66
	v_add_f32_e32 v18, v7, v18
	v_exp_f32_e32 v39, v11
	v_sub_f32_e32 v13, v13, v66
	v_add_f32_e32 v8, v36, v18
	v_exp_f32_e32 v87, v12
	v_sub_f32_e32 v14, v14, v66
	v_add_f32_e32 v8, v37, v8
	v_exp_f32_e32 v88, v13
	v_sub_f32_e32 v15, v15, v66
	v_add_f32_e32 v8, v38, v8
	v_exp_f32_e32 v89, v14
	v_sub_f32_e32 v16, v16, v66
	v_add_f32_e32 v8, v39, v8
	v_exp_f32_e32 v90, v15
	v_sub_f32_e32 v17, v17, v66
	v_add_f32_e32 v8, v87, v8
	v_exp_f32_e32 v91, v16
	v_sub_f32_e32 v70, v33, v66
	v_sub_f32_e32 v33, v19, v66
	v_add_f32_e32 v8, v88, v8
	v_exp_f32_e32 v92, v17
	v_cvt_pk_bf16_f32 v16, v0, v1
	v_cvt_pk_bf16_f32 v17, v2, v3
	v_cvt_pk_bf16_f32 v18, v4, v5
	v_cvt_pk_bf16_f32 v19, v6, v7
	ds_read_b128 v[0:3], v93
	v_add_f32_e32 v8, v89, v8
	v_exp_f32_e32 v94, v32
	v_add_f32_e32 v8, v90, v8
	v_add_f32_e32 v4, v91, v8
	v_sub_f32_e32 v71, v34, v66
	v_sub_f32_e32 v34, v20, v66
	v_add_f32_e32 v20, v92, v4
	v_sub_f32_e32 v72, v35, v66
	v_sub_f32_e32 v35, v21, v66
	v_sub_f32_e32 v77, v22, v66
	v_sub_f32_e32 v78, v23, v66
	v_sub_f32_e32 v79, v24, v66
	s_waitcnt lgkmcnt(0)
	v_mfma_f32_32x32x16_bf16 v[0:15], v[16:19], v[0:3], 0
	v_add_f32_e32 v24, v94, v20
	ds_read_b128 v[20:23], v96 offset:512
	v_exp_f32_e32 v95, v33
	v_exp_f32_e32 v98, v34
	v_exp_f32_e32 v99, v35
	ds_read_b128 v[32:35], v93 offset:32
	v_cvt_pk_bf16_f32 v36, v36, v37
	v_cvt_pk_bf16_f32 v37, v38, v39
	v_cvt_pk_bf16_f32 v38, v87, v88
	v_cvt_pk_bf16_f32 v39, v89, v90
	v_sub_f32_e32 v80, v25, v66
	v_sub_f32_e32 v81, v26, v66
	v_sub_f32_e32 v82, v27, v66
	v_sub_f32_e32 v83, v28, v66
	v_sub_f32_e32 v84, v29, v66
	v_sub_f32_e32 v85, v30, v66
	v_sub_f32_e32 v86, v31, v66
	v_add_f32_e32 v97, v95, v24
	s_waitcnt lgkmcnt(1)
	v_mfma_f32_32x32x16_bf16 v[16:31], v[16:19], v[20:23], 0
	v_exp_f32_e32 v77, v77
	v_exp_f32_e32 v78, v78
	v_add_f32_e32 v87, v98, v97
	v_add_f32_e32 v87, v99, v87
	v_add_f32_e32 v87, v77, v87
	v_exp_f32_e32 v79, v79
	v_add_f32_e32 v87, v78, v87
	s_waitcnt lgkmcnt(0)
	v_mfma_f32_32x32x16_bf16 v[0:15], v[36:39], v[32:35], v[0:15]
	ds_read_b128 v[32:35], v96 offset:544
	v_exp_f32_e32 v80, v80
	v_exp_f32_e32 v81, v81
	v_exp_f32_e32 v67, v67
	v_exp_f32_e32 v70, v70
	v_exp_f32_e32 v71, v71
	v_exp_f32_e32 v72, v72
	s_waitcnt lgkmcnt(0)
	v_mfma_f32_32x32x16_bf16 v[16:31], v[36:39], v[32:35], v[16:31]
	v_cvt_pk_bf16_f32 v32, v91, v92
	v_cvt_pk_bf16_f32 v33, v94, v95
	v_cvt_pk_bf16_f32 v34, v98, v99
	v_cvt_pk_bf16_f32 v35, v77, v78
	ds_read_b128 v[36:39], v93 offset:64
	v_exp_f32_e32 v78, v82
	v_exp_f32_e32 v82, v83
	s_waitcnt lgkmcnt(0)
	v_mfma_f32_32x32x16_bf16 v[0:15], v[32:35], v[36:39], v[0:15]
	ds_read_b128 v[36:39], v96 offset:576
	v_exp_f32_e32 v83, v84
	v_exp_f32_e32 v84, v85
	v_exp_f32_e32 v85, v86
	v_exp_f32_e32 v73, v73
	v_exp_f32_e32 v74, v74
	v_exp_f32_e32 v75, v75
	s_waitcnt lgkmcnt(0)
	v_mfma_f32_32x32x16_bf16 v[16:31], v[32:35], v[36:39], v[16:31]
	v_cvt_pk_bf16_f32 v32, v79, v80
	v_cvt_pk_bf16_f32 v33, v81, v78
	v_cvt_pk_bf16_f32 v34, v82, v83
	v_cvt_pk_bf16_f32 v35, v84, v85
	ds_read_b128 v[36:39], v93 offset:96
	v_exp_f32_e32 v76, v76
	v_sub_f32_e32 v40, v40, v66
	s_waitcnt lgkmcnt(0)
	v_mfma_f32_32x32x16_bf16 v[0:15], v[32:35], v[36:39], v[0:15]
	ds_read_b128 v[36:39], v96 offset:608
	v_sub_f32_e32 v41, v41, v66
	v_sub_f32_e32 v42, v42, v66
	v_sub_f32_e32 v43, v43, v66
	v_sub_f32_e32 v44, v44, v66
	v_sub_f32_e32 v45, v45, v66
	v_sub_f32_e32 v46, v46, v66
	s_waitcnt lgkmcnt(0)
; #define LAS __attribute__((address_space(3)))
; __device__ __forceinline__ void phase_attn(const Params& p, int S, int lgS, int B, int* counter, LAS unsigned char* lds) {
;     ...
;             for (int j = 0; j < 4; ++j)
; #pragma unroll
;                 for (int r = 0; r < 16; ++r) { pp[j][r] = __builtin_amdgcn_exp2f(pp[j][r]); ls += pp[j][r]; }
;             l_run += ls;
; #pragma unroll
;             for (int j = 0; j < 4; ++j)
; #pragma unroll
;                 for (int kk = 0; kk < 2; ++kk) {
;                     const int ks = 2 * j + kk;
;                     const bf16x8 pa = pack8(pp[j][8 * kk], pp[j][8 * kk + 1], pp[j][8 * kk + 2], pp[j][8 * kk + 3], pp[j][8 * kk + 4], pp[j][8 * kk + 5], pp[j][8 * kk + 6], pp[j][8 * kk + 7]);
;                     const u32x2 v0a = *(const LAS u32x2*)(vl + (16 * ks) * 2), v0b = *(const LAS u32x2*)(vl + (16 * ks + 8) * 2);
;                     const u32x2 v1a = *(const LAS u32x2*)(vl + (32 * 136 + 16 * ks) * 2), v1b = *(const LAS u32x2*)(vl + (32 * 136 + 16 * ks + 8) * 2);
;                     const u32x4 f0 = {v0a.x, v0a.y, v0b.x, v0b.y}, f1 = {v1a.x, v1a.y, v1b.x, v1b.y};
;                     o0 = __builtin_amdgcn_mfma_f32_32x32x16_bf16(pa, __builtin_bit_cast(bf16x8, f0), o0, 0, 0, 0);
;                     o1 = __builtin_amdgcn_mfma_f32_32x32x16_bf16(pa, __builtin_bit_cast(bf16x8, f1), o1, 0, 0, 0);
;                 }
;             if (t + 1 < NT) { LAS unsigned char* nb = lds + ((t + 1) & 1) * BUFB;
;                 *(LAS u32x4*)(nb + kdst) = kreg0; *(LAS u32x4*)(nb + kdst + 64 * 144) = kreg1; *(LAS u32x4*)(nb + vdst) = vreg0; *(LAS u32x4*)(nb + vdst + 128) = vreg1; }
;             __syncthreads();
	v_mfma_f32_32x32x16_bf16 v[16:31], v[32:35], v[36:39], v[16:31]
	v_cvt_pk_bf16_f32 v32, v67, v70
	v_cvt_pk_bf16_f32 v33, v71, v72
	v_cvt_pk_bf16_f32 v34, v73, v74
	v_cvt_pk_bf16_f32 v35, v75, v76
	ds_read_b128 v[36:39], v93 offset:128
	v_sub_f32_e32 v47, v47, v66
	v_exp_f32_e32 v40, v40
	s_waitcnt lgkmcnt(0)
	v_mfma_f32_32x32x16_bf16 v[0:15], v[32:35], v[36:39], v[0:15]
	ds_read_b128 v[36:39], v96 offset:640
	v_exp_f32_e32 v41, v41
	v_exp_f32_e32 v42, v42
	v_exp_f32_e32 v43, v43
	v_exp_f32_e32 v44, v44
	v_exp_f32_e32 v45, v45
	v_exp_f32_e32 v46, v46
	v_exp_f32_e32 v47, v47
	s_waitcnt lgkmcnt(0)
	v_mfma_f32_32x32x16_bf16 v[16:31], v[32:35], v[36:39], v[16:31]
	v_cvt_pk_bf16_f32 v32, v40, v41
	v_cvt_pk_bf16_f32 v33, v42, v43
	v_cvt_pk_bf16_f32 v34, v44, v45
	v_cvt_pk_bf16_f32 v35, v46, v47
	ds_read_b128 v[36:39], v93 offset:160
	v_sub_f32_e32 v48, v48, v66
	v_sub_f32_e32 v49, v49, v66
	v_sub_f32_e32 v50, v50, v66
	v_sub_f32_e32 v51, v51, v66
	v_sub_f32_e32 v52, v52, v66
	v_sub_f32_e32 v53, v53, v66
	v_sub_f32_e32 v54, v54, v66
	v_sub_f32_e32 v55, v55, v66
	s_waitcnt lgkmcnt(0)
	v_mfma_f32_32x32x16_bf16 v[0:15], v[32:35], v[36:39], v[0:15]
	ds_read_b128 v[36:39], v96 offset:672
	v_exp_f32_e32 v48, v48
	v_exp_f32_e32 v49, v49
	v_exp_f32_e32 v50, v50
	v_exp_f32_e32 v51, v51
	v_exp_f32_e32 v52, v52
	v_exp_f32_e32 v53, v53
	v_exp_f32_e32 v54, v54
	v_exp_f32_e32 v55, v55
	v_add_f32_e32 v87, v79, v87
	v_add_f32_e32 v77, v80, v87
	v_add_f32_e32 v77, v81, v77
	v_add_f32_e32 v77, v78, v77
	s_waitcnt lgkmcnt(0)
	v_mfma_f32_32x32x16_bf16 v[16:31], v[32:35], v[36:39], v[16:31]
	v_cvt_pk_bf16_f32 v32, v48, v49
	v_cvt_pk_bf16_f32 v33, v50, v51
	v_cvt_pk_bf16_f32 v34, v52, v53
	v_cvt_pk_bf16_f32 v35, v54, v55
	ds_read_b128 v[36:39], v93 offset:192
	v_add_f32_e32 v77, v82, v77
	v_add_f32_e32 v77, v83, v77
	v_add_f32_e32 v77, v84, v77
	v_add_f32_e32 v77, v85, v77
	v_sub_f32_e32 v56, v56, v66
	v_sub_f32_e32 v57, v57, v66
	v_sub_f32_e32 v58, v58, v66
	v_sub_f32_e32 v59, v59, v66
	v_sub_f32_e32 v60, v60, v66
	v_sub_f32_e32 v61, v61, v66
	v_sub_f32_e32 v62, v62, v66
	v_sub_f32_e32 v63, v63, v66
	v_add_f32_e32 v67, v67, v77
	s_waitcnt lgkmcnt(0)
	v_mfma_f32_32x32x16_bf16 v[0:15], v[32:35], v[36:39], v[0:15]
	ds_read_b128 v[36:39], v96 offset:704
	v_add_f32_e32 v67, v70, v67
	v_exp_f32_e32 v56, v56
	v_exp_f32_e32 v57, v57
	v_exp_f32_e32 v58, v58
	v_exp_f32_e32 v59, v59
	v_exp_f32_e32 v60, v60
	v_exp_f32_e32 v61, v61
	v_exp_f32_e32 v62, v62
	v_exp_f32_e32 v63, v63
	v_add_f32_e32 v67, v71, v67
	v_add_f32_e32 v67, v72, v67
	v_add_f32_e32 v67, v73, v67
	v_add_f32_e32 v67, v74, v67
	s_waitcnt lgkmcnt(0)
	v_mfma_f32_32x32x16_bf16 v[16:31], v[32:35], v[36:39], v[16:31]
	v_cvt_pk_bf16_f32 v32, v56, v57
	v_cvt_pk_bf16_f32 v33, v58, v59
	v_cvt_pk_bf16_f32 v34, v60, v61
	v_cvt_pk_bf16_f32 v35, v62, v63
	ds_read_b128 v[36:39], v93 offset:224
	v_add_f32_e32 v67, v75, v67
	v_add_f32_e32 v67, v76, v67
	v_add_f32_e32 v40, v40, v67
	v_add_f32_e32 v40, v41, v40
	s_waitcnt lgkmcnt(0)
	v_mfma_f32_32x32x16_bf16 v[0:15], v[32:35], v[36:39], v[0:15]
	v_add_f32_e32 v36, v42, v40
	v_add_f32_e32 v40, v43, v36
	ds_read_b128 v[36:39], v96 offset:736
	v_add_f32_e32 v40, v44, v40
	v_add_f32_e32 v40, v45, v40
	v_add_f32_e32 v40, v46, v40
	v_add_f32_e32 v40, v47, v40
	s_waitcnt lgkmcnt(0)
	v_mfma_f32_32x32x16_bf16 v[16:31], v[32:35], v[36:39], v[16:31]
	v_add_f32_e32 v32, v48, v40
	v_add_f32_e32 v32, v49, v32
	v_add_f32_e32 v32, v50, v32
	v_add_f32_e32 v32, v51, v32
	v_add_f32_e32 v32, v52, v32
	v_add_f32_e32 v32, v53, v32
	v_add_f32_e32 v32, v54, v32
	v_add_f32_e32 v32, v55, v32
	v_add_f32_e32 v32, v56, v32
	v_add_f32_e32 v32, v57, v32
	v_add_f32_e32 v32, v58, v32
	v_add_f32_e32 v32, v59, v32
	v_add_f32_e32 v32, v60, v32
	v_add_f32_e32 v32, v61, v32
	v_add_f32_e32 v32, v62, v32
	v_add_f32_e32 v67, v63, v32
	v_pk_add_f32 v[194:195], v[66:67], 0 op_sel_hi:[1,0]
	s_waitcnt vmcnt(3)
	ds_write_b128 v68, v[128:131] offset:35840
	s_waitcnt vmcnt(2)
	ds_write_b128 v68, v[132:135] offset:45056
	s_waitcnt vmcnt(1)
	v_add_u32_e32 v224, 0x8c00, v69
	ds_write2_b64 v224, v[136:137], v[138:139] offset1:2
	s_waitcnt vmcnt(0)
	ds_write2_b64 v224, v[140:141], v[142:143] offset0:16 offset1:18
	v_pk_add_f32 v[32:33], v[194:195], 0 neg_lo:[1,1] neg_hi:[1,1]
	s_waitcnt lgkmcnt(0)
	v_mov_b32_e32 v33, v32
	v_mov_b32_e32 v34, v32
	v_mov_b32_e32 v35, v32
	v_mov_b32_e32 v36, v32
	v_mov_b32_e32 v37, v32
	v_mov_b32_e32 v38, v32
	v_mov_b32_e32 v39, v32
	v_mov_b32_e32 v40, v32
	v_mov_b32_e32 v41, v32
	v_mov_b32_e32 v42, v32
	v_mov_b32_e32 v43, v32
	v_mov_b32_e32 v44, v32
	v_mov_b32_e32 v45, v32
	v_mov_b32_e32 v46, v32
	v_mov_b32_e32 v47, v32
	s_barrier

; #define LAS __attribute__((address_space(3)))
; #define LDS_WAIT() asm volatile("s_waitcnt lgkmcnt(0)" ::: "memory")
; __device__ __forceinline__ int crow(int r, int hi) { return (r & 3) + 8 * (r >> 2) + 4 * hi; }
; __device__ __forceinline__ void phase_attn(const Params& p, int S, int lgS, int B, int* counter, LAS unsigned char* lds) {
;     ...
;         for (int t = 0; t < NT; ++t) {
;             const LAS unsigned char* kb = lds + (t & 1) * BUFB; const LAS unsigned char* vb = kb + KB;
;             if (t + 1 < NT) { const bf16_t* kn = ksrc + (size_t)(t + 1) * 128 * 2048; const bf16_t* vn_ = vsrc + (t + 1) * 128;
;                 kreg0 = *(const u32x4*)kn; kreg1 = *(const u32x4*)(kn + (size_t)64 * 2048); vreg0 = *(const u32x4*)vn_; vreg1 = *(const u32x4*)(vn_ + 64); }
;             f32x16 pp[4] = {negm, negm, negm, negm};
;             const LAS unsigned char* kl = kb + klane; const LAS unsigned char* vl = vb + vlane;
; #pragma unroll
;             for (int d0 = 0; d0 < 4; ++d0)
; #pragma unroll
;                 for (int j = 0; j < 4; ++j) { const bf16x8 a = *(const LAS bf16x8*)(kl + (32 * j * 72 + 16 * d0) * 2); pp[j] = __builtin_amdgcn_mfma_f32_32x32x16_bf16(a, qr[d0], pp[j], 0, 0, 0); }
;             float mxa = fmaxf(pp[0][0], pp[1][0]), mxb = fmaxf(pp[2][0], pp[3][0]);
; #pragma unroll
;             for (int r = 1; r < 16; ++r) { mxa = fmaxf(fmaxf(mxa, pp[0][r]), pp[1][r]); mxb = fmaxf(fmaxf(mxb, pp[2][r]), pp[3][r]); }
;             float mx = fmaxf(mxa, mxb);
;             mx = fmaxf(mx, shx(mx, 32, lane));
;             const bool first = (t == 0);
;             if (first || __any(mx > 8.f)) {
;                 const float d = first ? mx : fmaxf(mx, 0.f);
;                 m_run += d;
; #pragma unroll
;                 for (int j = 0; j < 4; ++j)
; #pragma unroll
;                     for (int r = 0; r < 16; ++r) pp[j][r] -= d;
; #pragma unroll
;                 for (int r = 0; r < 16; ++r) negm[r] = -m_run;
;                 if (!first) {
;                     const float alpha = __builtin_amdgcn_exp2f(-d); l_run *= alpha;
;                     if (hi == 0) wsf[r32] = alpha;
;                     LDS_WAIT();
; #pragma unroll
;                     for (int r = 0; r < 16; ++r) { const float f = wsf[crow(r, hi)]; o0[r] *= f; o1[r] *= f; }
;                     LDS_WAIT();
;                 }
;             }
.LBB0_731:
	s_bitcmp1_b32 s18, 0
	s_cselect_b32 s18, 0x8c00, 0
	s_add_i32 s18, s18, 0
	v_add_u32_e32 v155, s18, v198
	ds_read_b128 v[224:227], v155
	ds_read_b128 v[228:231], v155 offset:4608
	ds_read_b128 v[232:235], v155 offset:9216
	ds_read_b128 v[242:245], v155 offset:13824
	s_mov_b32 s19, 0x41000000
	s_waitcnt lgkmcnt(3)
	v_mfma_f32_32x32x16_bf16 v[96:111], v[224:227], v[112:115], v[32:47]
	ds_read_b128 v[224:227], v155 offset:32
	s_waitcnt lgkmcnt(3)
	v_mfma_f32_32x32x16_bf16 v[80:95], v[228:231], v[112:115], v[32:47]
	ds_read_b128 v[228:231], v155 offset:4640
	s_waitcnt lgkmcnt(3)
	v_mfma_f32_32x32x16_bf16 v[64:79], v[232:235], v[112:115], v[32:47]
	ds_read_b128 v[232:235], v155 offset:9248
	s_waitcnt lgkmcnt(3)
	v_mfma_f32_32x32x16_bf16 v[48:63], v[242:245], v[112:115], v[32:47]
	ds_read_b128 v[242:245], v155 offset:13856
	s_waitcnt lgkmcnt(3)
	v_mfma_f32_32x32x16_bf16 v[96:111], v[224:227], v[116:119], v[96:111]
	ds_read_b128 v[224:227], v155 offset:64
	s_waitcnt lgkmcnt(3)
	v_mfma_f32_32x32x16_bf16 v[80:95], v[228:231], v[116:119], v[80:95]
	ds_read_b128 v[228:231], v155 offset:4672
	s_waitcnt lgkmcnt(3)
	v_mfma_f32_32x32x16_bf16 v[64:79], v[232:235], v[116:119], v[64:79]
	ds_read_b128 v[232:235], v155 offset:9280
	s_waitcnt lgkmcnt(3)
	v_mfma_f32_32x32x16_bf16 v[48:63], v[242:245], v[116:119], v[48:63]
	ds_read_b128 v[242:245], v155 offset:13888
	s_waitcnt lgkmcnt(3)
	v_mfma_f32_32x32x16_bf16 v[96:111], v[224:227], v[120:123], v[96:111]
	ds_read_b128 v[224:227], v155 offset:96
	s_waitcnt lgkmcnt(3)
	v_mfma_f32_32x32x16_bf16 v[80:95], v[228:231], v[120:123], v[80:95]
	ds_read_b128 v[228:231], v155 offset:4704
	s_waitcnt lgkmcnt(3)
	v_mfma_f32_32x32x16_bf16 v[64:79], v[232:235], v[120:123], v[64:79]
	ds_read_b128 v[232:235], v155 offset:9312
	s_waitcnt lgkmcnt(3)
	v_mfma_f32_32x32x16_bf16 v[48:63], v[242:245], v[120:123], v[48:63]
	ds_read_b128 v[242:245], v155 offset:13920
	s_waitcnt lgkmcnt(3)
	v_mfma_f32_32x32x16_bf16 v[96:111], v[224:227], v[124:127], v[96:111]
	s_waitcnt lgkmcnt(2)
	v_mfma_f32_32x32x16_bf16 v[80:95], v[228:231], v[124:127], v[80:95]
	s_waitcnt lgkmcnt(1)
	v_mfma_f32_32x32x16_bf16 v[64:79], v[232:235], v[124:127], v[64:79]
	s_waitcnt lgkmcnt(0)
	v_mfma_f32_32x32x16_bf16 v[48:63], v[242:245], v[124:127], v[48:63]
	s_nop 10
	v_max_f32_e32 v157, v64, v64
	v_max_f32_e32 v155, v48, v48
	v_max_f32_e32 v155, v157, v155
	v_max3_f32 v155, v155, v65, v49
	v_max3_f32 v155, v155, v66, v50
	v_max3_f32 v155, v155, v67, v51
	v_max3_f32 v155, v155, v68, v52
	v_max3_f32 v155, v155, v69, v53
	v_max3_f32 v157, v96, v80, v97
	v_max3_f32 v157, v157, v81, v98
	v_max3_f32 v157, v157, v82, v99
	v_max3_f32 v157, v157, v83, v100
	v_max3_f32 v157, v157, v84, v101
	v_max3_f32 v157, v157, v85, v102
	v_max3_f32 v155, v155, v70, v54
	v_max3_f32 v157, v157, v86, v103
	v_max3_f32 v155, v155, v71, v55
	v_max3_f32 v157, v157, v87, v104
	v_max3_f32 v155, v155, v72, v56
	v_max3_f32 v157, v157, v88, v105
	v_max3_f32 v155, v155, v73, v57
	v_max3_f32 v157, v157, v89, v106
	v_max3_f32 v155, v155, v74, v58
	v_max3_f32 v157, v157, v90, v107
	v_max3_f32 v155, v155, v75, v59
	v_max3_f32 v157, v157, v91, v108
	v_max3_f32 v155, v155, v76, v60
	v_max3_f32 v157, v157, v92, v109
	v_max3_f32 v155, v155, v77, v61
	v_max3_f32 v157, v157, v93, v110
	v_max3_f32 v155, v155, v78, v62
	v_max3_f32 v157, v157, v94, v111
	v_max3_f32 v155, v155, v79, v63
	v_max3_f32 v155, v157, v95, v155
	ds_bpermute_b32 v157, v209, v155
	s_waitcnt lgkmcnt(0)
	v_max_f32_e32 v157, v157, v157
	v_max_f32_e32 v155, v155, v157
	v_cmp_lt_f32_e32 vcc, s19, v155
	s_cbranch_vccz .LBB0_735
	v_max_f32_e32 v32, v155, v155
	v_max_f32_e32 v32, 0, v32
	v_exp_f32_e64 v33, -v32
	s_and_saveexec_b64 s[50:51], s[4:5]
	ds_write_b32 v219, v33
	s_or_b64 exec, exec, s[50:51]
	s_waitcnt lgkmcnt(0)
	v_pk_add_f32 v[96:97], v[96:97], v[32:33] op_sel_hi:[1,0] neg_lo:[0,1] neg_hi:[0,1]
	v_pk_add_f32 v[98:99], v[98:99], v[32:33] op_sel_hi:[1,0] neg_lo:[0,1] neg_hi:[0,1]
	v_pk_add_f32 v[100:101], v[100:101], v[32:33] op_sel_hi:[1,0] neg_lo:[0,1] neg_hi:[0,1]
	v_pk_add_f32 v[102:103], v[102:103], v[32:33] op_sel_hi:[1,0] neg_lo:[0,1] neg_hi:[0,1]
	v_pk_add_f32 v[104:105], v[104:105], v[32:33] op_sel_hi:[1,0] neg_lo:[0,1] neg_hi:[0,1]
	v_pk_add_f32 v[106:107], v[106:107], v[32:33] op_sel_hi:[1,0] neg_lo:[0,1] neg_hi:[0,1]
	v_pk_add_f32 v[108:109], v[108:109], v[32:33] op_sel_hi:[1,0] neg_lo:[0,1] neg_hi:[0,1]
	v_pk_add_f32 v[110:111], v[110:111], v[32:33] op_sel_hi:[1,0] neg_lo:[0,1] neg_hi:[0,1]
	v_pk_add_f32 v[80:81], v[80:81], v[32:33] op_sel_hi:[1,0] neg_lo:[0,1] neg_hi:[0,1]
	v_pk_add_f32 v[82:83], v[82:83], v[32:33] op_sel_hi:[1,0] neg_lo:[0,1] neg_hi:[0,1]
	v_pk_add_f32 v[84:85], v[84:85], v[32:33] op_sel_hi:[1,0] neg_lo:[0,1] neg_hi:[0,1]
	v_pk_add_f32 v[86:87], v[86:87], v[32:33] op_sel_hi:[1,0] neg_lo:[0,1] neg_hi:[0,1]
	v_pk_add_f32 v[88:89], v[88:89], v[32:33] op_sel_hi:[1,0] neg_lo:[0,1] neg_hi:[0,1]
	v_pk_add_f32 v[90:91], v[90:91], v[32:33] op_sel_hi:[1,0] neg_lo:[0,1] neg_hi:[0,1]
	v_pk_add_f32 v[92:93], v[92:93], v[32:33] op_sel_hi:[1,0] neg_lo:[0,1] neg_hi:[0,1]
	v_pk_add_f32 v[94:95], v[94:95], v[32:33] op_sel_hi:[1,0] neg_lo:[0,1] neg_hi:[0,1]
	v_pk_add_f32 v[64:65], v[64:65], v[32:33] op_sel_hi:[1,0] neg_lo:[0,1] neg_hi:[0,1]
	v_pk_add_f32 v[66:67], v[66:67], v[32:33] op_sel_hi:[1,0] neg_lo:[0,1] neg_hi:[0,1]
	v_pk_add_f32 v[68:69], v[68:69], v[32:33] op_sel_hi:[1,0] neg_lo:[0,1] neg_hi:[0,1]
	v_pk_add_f32 v[70:71], v[70:71], v[32:33] op_sel_hi:[1,0] neg_lo:[0,1] neg_hi:[0,1]
	v_pk_add_f32 v[72:73], v[72:73], v[32:33] op_sel_hi:[1,0] neg_lo:[0,1] neg_hi:[0,1]
	v_pk_add_f32 v[74:75], v[74:75], v[32:33] op_sel_hi:[1,0] neg_lo:[0,1] neg_hi:[0,1]
	v_pk_add_f32 v[76:77], v[76:77], v[32:33] op_sel_hi:[1,0] neg_lo:[0,1] neg_hi:[0,1]
	v_pk_add_f32 v[78:79], v[78:79], v[32:33] op_sel_hi:[1,0] neg_lo:[0,1] neg_hi:[0,1]
	v_pk_add_f32 v[48:49], v[48:49], v[32:33] op_sel_hi:[1,0] neg_lo:[0,1] neg_hi:[0,1]
	v_pk_add_f32 v[50:51], v[50:51], v[32:33] op_sel_hi:[1,0] neg_lo:[0,1] neg_hi:[0,1]
	v_pk_add_f32 v[52:53], v[52:53], v[32:33] op_sel_hi:[1,0] neg_lo:[0,1] neg_hi:[0,1]
	v_pk_add_f32 v[54:55], v[54:55], v[32:33] op_sel_hi:[1,0] neg_lo:[0,1] neg_hi:[0,1]
	v_pk_add_f32 v[56:57], v[56:57], v[32:33] op_sel_hi:[1,0] neg_lo:[0,1] neg_hi:[0,1]
	v_pk_add_f32 v[58:59], v[58:59], v[32:33] op_sel_hi:[1,0] neg_lo:[0,1] neg_hi:[0,1]
	v_pk_add_f32 v[60:61], v[60:61], v[32:33] op_sel_hi:[1,0] neg_lo:[0,1] neg_hi:[0,1]
	v_pk_add_f32 v[62:63], v[62:63], v[32:33] op_sel_hi:[1,0] neg_lo:[0,1] neg_hi:[0,1]
	v_pk_add_f32 v[196:197], v[194:195], v[32:33]
	v_pk_mul_f32 v[44:45], v[194:195], v[32:33]
	ds_read_b128 v[32:35], v222 offset:64
	ds_read_b128 v[36:39], v222 offset:96
	ds_read_b128 v[40:43], v222
	ds_read_b128 v[224:227], v222 offset:32
	v_mov_b32_e32 v197, v45
	s_waitcnt lgkmcnt(0)
; #define LAS __attribute__((address_space(3)))
; #define LDS_WAIT() asm volatile("s_waitcnt lgkmcnt(0)" ::: "memory")
; __device__ __forceinline__ int crow(int r, int hi) { return (r & 3) + 8 * (r >> 2) + 4 * hi; }
; __device__ __forceinline__ void phase_attn(const Params& p, int S, int lgS, int B, int* counter, LAS unsigned char* lds) {
;     ...
;                 if (!first) {
;                     const float alpha = __builtin_amdgcn_exp2f(-d); l_run *= alpha;
;                     if (hi == 0) wsf[r32] = alpha;
;                     LDS_WAIT();
; #pragma unroll
;                     for (int r = 0; r < 16; ++r) { const float f = wsf[crow(r, hi)]; o0[r] *= f; o1[r] *= f; }
;                     LDS_WAIT();
;                 }
;             }
;             float ls = 0.f;
; #pragma unroll
;             for (int j = 0; j < 4; ++j)
; #pragma unroll
;                 for (int r = 0; r < 16; ++r) { pp[j][r] = __builtin_amdgcn_exp2f(pp[j][r]); ls += pp[j][r]; }
;             l_run += ls;
; #pragma unroll
;             for (int j = 0; j < 4; ++j)
; #pragma unroll
;                 for (int kk = 0; kk < 2; ++kk) {
;                     const int ks = 2 * j + kk;
;                     const bf16x8 pa = pack8(pp[j][8 * kk], pp[j][8 * kk + 1], pp[j][8 * kk + 2], pp[j][8 * kk + 3], pp[j][8 * kk + 4], pp[j][8 * kk + 5], pp[j][8 * kk + 6], pp[j][8 * kk + 7]);
;                     const u32x2 v0a = *(const LAS u32x2*)(vl + (16 * ks) * 2), v0b = *(const LAS u32x2*)(vl + (16 * ks + 8) * 2);
;                     const u32x2 v1a = *(const LAS u32x2*)(vl + (32 * 136 + 16 * ks) * 2), v1b = *(const LAS u32x2*)(vl + (32 * 136 + 16 * ks + 8) * 2);
;                     const u32x4 f0 = {v0a.x, v0a.y, v0b.x, v0b.y}, f1 = {v1a.x, v1a.y, v1b.x, v1b.y};
;                     o0 = __builtin_amdgcn_mfma_f32_32x32x16_bf16(pa, __builtin_bit_cast(bf16x8, f0), o0, 0, 0, 0);
;                     o1 = __builtin_amdgcn_mfma_f32_32x32x16_bf16(pa, __builtin_bit_cast(bf16x8, f1), o1, 0, 0, 0);
;                 }
;             if (t + 1 < NT) { LAS unsigned char* nb = lds + ((t + 1) & 1) * BUFB;
;                 *(LAS u32x4*)(nb + kdst) = kreg0; *(LAS u32x4*)(nb + kdst + 64 * 144) = kreg1; *(LAS u32x4*)(nb + vdst) = vreg0; *(LAS u32x4*)(nb + vdst + 128) = vreg1; }
	v_pk_add_f32 v[46:47], v[196:197], 0 neg_lo:[1,1] neg_hi:[1,1]
	s_waitcnt lgkmcnt(2)
	v_pk_mul_f32 v[12:13], v[12:13], v[36:37]
	v_pk_mul_f32 v[8:9], v[8:9], v[32:33]
	s_waitcnt lgkmcnt(0)
	v_pk_mul_f32 v[4:5], v[4:5], v[224:225]
	v_pk_mul_f32 v[14:15], v[14:15], v[38:39]
	v_pk_mul_f32 v[10:11], v[10:11], v[34:35]
	v_pk_mul_f32 v[6:7], v[6:7], v[226:227]
	v_pk_mul_f32 v[2:3], v[2:3], v[42:43]
	v_pk_mul_f32 v[0:1], v[0:1], v[40:41]
	v_pk_mul_f32 v[28:29], v[28:29], v[36:37]
	v_pk_mul_f32 v[24:25], v[24:25], v[32:33]
	v_pk_mul_f32 v[20:21], v[20:21], v[224:225]
	v_pk_mul_f32 v[30:31], v[30:31], v[38:39]
	v_pk_mul_f32 v[26:27], v[26:27], v[34:35]
	v_pk_mul_f32 v[22:23], v[22:23], v[226:227]
	v_pk_mul_f32 v[18:19], v[18:19], v[42:43]
	v_pk_mul_f32 v[16:17], v[16:17], v[40:41]
	v_mov_b32_e32 v47, v46
	v_mov_b32_e32 v45, v46
	v_mov_b32_e32 v44, v46
	v_mov_b32_e32 v43, v46
	v_mov_b32_e32 v42, v46
	v_mov_b32_e32 v41, v46
	v_mov_b32_e32 v40, v46
	v_mov_b32_e32 v39, v46
	v_mov_b32_e32 v38, v46
	v_mov_b32_e32 v37, v46
	v_mov_b32_e32 v36, v46
	v_mov_b32_e32 v35, v46
	v_mov_b32_e32 v34, v46
	v_mov_b32_e32 v33, v46
	v_mov_b32_e32 v32, v46
	v_mov_b64_e32 v[194:195], v[196:197]
.LBB0_735:
	v_exp_f32_e32 v96, v96
	v_exp_f32_e32 v97, v97
	v_exp_f32_e32 v98, v98
	v_exp_f32_e32 v99, v99
	v_exp_f32_e32 v100, v100
	v_exp_f32_e32 v101, v101
	v_exp_f32_e32 v102, v102
	v_exp_f32_e32 v103, v103
	v_add3_u32 v155, s18, v186, v199
	v_add_u32_e32 v157, 0x4800, v155
	v_add_u32_e32 v155, 0x6800, v155
	v_cvt_pk_bf16_f32 v224, v96, v97
	v_cvt_pk_bf16_f32 v225, v98, v99
	v_cvt_pk_bf16_f32 v226, v100, v101
	v_cvt_pk_bf16_f32 v227, v102, v103
	ds_read_b128 v[228:231], v157
	ds_read_b128 v[232:235], v157 offset:32
	ds_read_b128 v[242:245], v155 offset:512
	v_exp_f32_e32 v104, v104
	v_exp_f32_e32 v105, v105
	v_exp_f32_e32 v106, v106
	v_exp_f32_e32 v107, v107
	v_exp_f32_e32 v108, v108
	v_exp_f32_e32 v109, v109
	v_exp_f32_e32 v110, v110
	v_exp_f32_e32 v111, v111
	s_waitcnt lgkmcnt(2)
	v_mfma_f32_32x32x16_bf16 v[0:15], v[224:227], v[228:231], v[0:15]
	ds_read_b128 v[228:231], v155 offset:544
	v_exp_f32_e32 v80, v80
	v_exp_f32_e32 v81, v81
	v_exp_f32_e32 v82, v82
	v_exp_f32_e32 v83, v83
	v_exp_f32_e32 v84, v84
	v_exp_f32_e32 v85, v85
	s_waitcnt lgkmcnt(1)
	v_mfma_f32_32x32x16_bf16 v[16:31], v[224:227], v[242:245], v[16:31]
	v_cvt_pk_bf16_f32 v224, v104, v105
	v_cvt_pk_bf16_f32 v225, v106, v107
	v_cvt_pk_bf16_f32 v226, v108, v109
	v_cvt_pk_bf16_f32 v227, v110, v111
	v_exp_f32_e32 v86, v86
	v_exp_f32_e32 v87, v87
	v_exp_f32_e32 v88, v88
	v_mfma_f32_32x32x16_bf16 v[0:15], v[224:227], v[232:235], v[0:15]
	v_exp_f32_e32 v89, v89
	v_exp_f32_e32 v90, v90
	v_exp_f32_e32 v91, v91
	v_exp_f32_e32 v92, v92
	v_exp_f32_e32 v93, v93
	v_exp_f32_e32 v94, v94
	v_exp_f32_e32 v95, v95
	s_waitcnt lgkmcnt(0)
	v_mfma_f32_32x32x16_bf16 v[16:31], v[224:227], v[228:231], v[16:31]
	v_cvt_pk_bf16_f32 v224, v80, v81
	v_cvt_pk_bf16_f32 v225, v82, v83
	v_cvt_pk_bf16_f32 v226, v84, v85
	v_cvt_pk_bf16_f32 v227, v86, v87
	ds_read_b128 v[228:231], v157 offset:64
	ds_read_b128 v[232:235], v155 offset:576
	v_exp_f32_e32 v64, v64
	v_exp_f32_e32 v65, v65
	s_waitcnt lgkmcnt(1)
	v_mfma_f32_32x32x16_bf16 v[0:15], v[224:227], v[228:231], v[0:15]
	v_exp_f32_e32 v66, v66
	v_exp_f32_e32 v67, v67
	v_exp_f32_e32 v68, v68
	v_exp_f32_e32 v69, v69
	v_exp_f32_e32 v70, v70
	v_exp_f32_e32 v71, v71
	v_exp_f32_e32 v72, v72
	s_waitcnt lgkmcnt(0)
	v_mfma_f32_32x32x16_bf16 v[16:31], v[224:227], v[232:235], v[16:31]
	v_cvt_pk_bf16_f32 v224, v88, v89
	v_cvt_pk_bf16_f32 v225, v90, v91
	v_cvt_pk_bf16_f32 v226, v92, v93
	v_cvt_pk_bf16_f32 v227, v94, v95
	ds_read_b128 v[228:231], v157 offset:96
	ds_read_b128 v[232:235], v155 offset:608
	v_exp_f32_e32 v73, v73
	v_exp_f32_e32 v74, v74
	s_waitcnt lgkmcnt(1)
	v_mfma_f32_32x32x16_bf16 v[0:15], v[224:227], v[228:231], v[0:15]
	v_exp_f32_e32 v75, v75
	v_exp_f32_e32 v76, v76
	v_exp_f32_e32 v77, v77
	v_exp_f32_e32 v78, v78
	v_exp_f32_e32 v79, v79
	v_exp_f32_e32 v48, v48
	v_exp_f32_e32 v49, v49
	s_waitcnt lgkmcnt(0)
	v_mfma_f32_32x32x16_bf16 v[16:31], v[224:227], v[232:235], v[16:31]
	v_cvt_pk_bf16_f32 v224, v64, v65
	v_cvt_pk_bf16_f32 v225, v66, v67
	v_cvt_pk_bf16_f32 v226, v68, v69
	v_cvt_pk_bf16_f32 v227, v70, v71
	ds_read_b128 v[228:231], v157 offset:128
	ds_read_b128 v[232:235], v155 offset:640
	v_exp_f32_e32 v50, v50
	v_exp_f32_e32 v51, v51
	s_waitcnt lgkmcnt(1)
	v_mfma_f32_32x32x16_bf16 v[0:15], v[224:227], v[228:231], v[0:15]
	v_exp_f32_e32 v52, v52
	v_exp_f32_e32 v53, v53
	v_exp_f32_e32 v54, v54
	v_exp_f32_e32 v55, v55
	v_exp_f32_e32 v56, v56
	v_exp_f32_e32 v57, v57
	v_exp_f32_e32 v58, v58
	s_waitcnt lgkmcnt(0)
	v_mfma_f32_32x32x16_bf16 v[16:31], v[224:227], v[232:235], v[16:31]
	v_cvt_pk_bf16_f32 v224, v72, v73
	v_cvt_pk_bf16_f32 v225, v74, v75
	v_cvt_pk_bf16_f32 v226, v76, v77
	v_cvt_pk_bf16_f32 v227, v78, v79
	ds_read_b128 v[228:231], v157 offset:160
	ds_read_b128 v[232:235], v155 offset:672
	v_exp_f32_e32 v59, v59
	v_exp_f32_e32 v60, v60
	s_waitcnt lgkmcnt(1)
	v_mfma_f32_32x32x16_bf16 v[0:15], v[224:227], v[228:231], v[0:15]
	v_exp_f32_e32 v61, v61
	v_exp_f32_e32 v62, v62
	v_exp_f32_e32 v63, v63
	s_andn2_b64 vcc, exec, s[26:27]
	s_waitcnt lgkmcnt(0)
	v_mfma_f32_32x32x16_bf16 v[16:31], v[224:227], v[232:235], v[16:31]
	v_cvt_pk_bf16_f32 v224, v48, v49
	v_cvt_pk_bf16_f32 v225, v50, v51
	v_cvt_pk_bf16_f32 v226, v52, v53
	v_cvt_pk_bf16_f32 v227, v54, v55
	ds_read_b128 v[228:231], v157 offset:192
	ds_read_b128 v[232:235], v155 offset:704
	s_waitcnt lgkmcnt(1)
	v_mfma_f32_32x32x16_bf16 v[0:15], v[224:227], v[228:231], v[0:15]
	s_waitcnt lgkmcnt(0)
	v_mfma_f32_32x32x16_bf16 v[16:31], v[224:227], v[232:235], v[16:31]
	v_cvt_pk_bf16_f32 v224, v56, v57
	v_cvt_pk_bf16_f32 v225, v58, v59
	v_cvt_pk_bf16_f32 v226, v60, v61
	v_cvt_pk_bf16_f32 v227, v62, v63
	ds_read_b128 v[228:231], v157 offset:224
	ds_read_b128 v[232:235], v155 offset:736
	s_waitcnt lgkmcnt(1)
	v_mfma_f32_32x32x16_bf16 v[0:15], v[224:227], v[228:231], v[0:15]
	s_waitcnt lgkmcnt(0)
	v_mfma_f32_32x32x16_bf16 v[16:31], v[224:227], v[232:235], v[16:31]
	s_cbranch_vccnz .LBB0_737
	s_bitcmp1_b32 s17, 0
	s_cselect_b32 s18, 0x8c00, 0
	s_add_i32 s18, s18, 0
	v_add_u32_e32 v155, s18, v145
	v_add_u32_e32 v157, s18, v149
	s_waitcnt vmcnt(3)
	ds_write_b128 v155, v[128:131]
	s_waitcnt vmcnt(2)
	ds_write_b128 v155, v[132:135] offset:9216
	s_waitcnt vmcnt(1)
	ds_write2_b64 v157, v[136:137], v[138:139] offset1:2
	s_waitcnt vmcnt(0)
	ds_write2_b64 v157, v[140:141], v[142:143] offset0:16 offset1:18

; #define PG8_STAGE(bufoff, gbase, voff) do { _Pragma("unroll") for (int _i = 0; _i < 2; ++_i) \
;         __builtin_amdgcn_global_load_lds((const unsigned*)((const char*)(gbase) + (voff)[_i]), (LAS unsigned*)(lds + (bufoff) + ldsw + _i * 8192), 16, 0, 0); } while (0)
; #define PG8_LDA(dst, b, h) do { _Pragma("unroll") for (int m = 0; m < 4; ++m) _Pragma("unroll") for (int k = 0; k < 2; ++k) dst[m][k] = *(const LAS bf16x8*)(lds + PG8_SA(b, h) + aoff + m * 2048 + k * 1024); } while (0)
; #define PG8_LDB(dst, b, h) do { _Pragma("unroll") for (int n = 0; n < 2; ++n) _Pragma("unroll") for (int k = 0; k < 2; ++k) dst[n][k] = *(const LAS bf16x8*)(lds + PG8_SB(b, h) + boff + n * 2048 + k * 1024); } while (0)
; #define PG8_MMA(ai, bj, At, Bt) do { __builtin_amdgcn_s_setprio(1); _Pragma("unroll") for (int m = 0; m < 4; ++m) _Pragma("unroll") for (int n = 0; n < 2; ++n) _Pragma("unroll") for (int k = 0; k < 2; ++k) \
;         acc[ai][bj][m][n] = __builtin_amdgcn_mfma_f32_16x16x32_bf16(Bt[n][k], At[m][k], acc[ai][bj][m][n], 0, 0, 0); __builtin_amdgcn_s_setprio(0); } while (0)
; #define PG8_WAIT_V(n) asm volatile("s_waitcnt vmcnt(" #n ")" ::: "memory")
; #define PG8_WAIT_L(n) asm volatile("s_waitcnt lgkmcnt(" #n ")" ::: "memory")
; #define PG8_BAR __builtin_amdgcn_s_barrier()
; #define PG8_SCHED __builtin_amdgcn_sched_barrier(0)
; template <class Epi, class Addr>
; __device__ __forceinline__ void gemm_phase(LAS unsigned char* lds, const Gemm g, const StaticOrder& S, const Addr& AD, const Epi& E) {
;     ...
;         for (int t = 0; t < nt; t += 2) {
;             const bool last = (t == nt - 2);
;             const char* a1 = cA + (size_t)(t + 1) * kstep;
;             const char* a2 = last ? nA : cA + (size_t)(t + 2) * kstep; const char* b2 = last ? nB : cB + (size_t)(t + 2) * kstep;
;             const char* a3 = a2 + kstep; const char* b3 = b2 + kstep;
;             PG8_LDB(B0, 0, 0); PG8_LDB(B1, 0, 1); PG8_SCHED; PG8_LDA(At, 0, 0); PG8_STAGE(PG8_SA(1, 1), a1 + hstepA, voffA);
;             PG8_WAIT_V(8); PG8_WAIT_L(0); PG8_BAR; PG8_MMA(0, 0, At, B0); PG8_MMA(0, 1, At, B1); PG8_BAR; PG8_SCHED;
;             PG8_LDA(At, 0, 1); PG8_STAGE(PG8_SB(0, 0), b2, voffB); PG8_STAGE(PG8_SB(0, 1), b2 + hstepB, voffB); PG8_STAGE(PG8_SA(0, 0), a2, voffA);
;             PG8_WAIT_V(8); PG8_WAIT_L(0); PG8_BAR; PG8_MMA(1, 0, At, B0); PG8_MMA(1, 1, At, B1); PG8_BAR; PG8_SCHED;
.LBB0_1256:
	s_add_i32 s76, s64, 2
	s_add_u32 s24, s62, 0xfffc0080
	s_addc_u32 s25, s63, -1
	s_add_i32 s28, 0, 0x10000
	s_cmp_eq_u32 s70, s64
	s_cselect_b32 s67, s55, s25
	s_cselect_b32 s66, s57, s24
	s_cselect_b32 s65, s72, s75
	s_cselect_b32 s64, s73, s74
	s_add_i32 s24, 0, 0x14000
	v_add_u32_e32 v140, s28, v186
	v_add_u32_e32 v166, s24, v186
	ds_read_b128 v[128:131], v140
	ds_read_b128 v[132:135], v140 offset:1024
	ds_read_b128 v[136:139], v140 offset:2048
	ds_read_b128 v[140:143], v140 offset:3072
	ds_read_b128 v[144:147], v166
	ds_read_b128 v[148:151], v166 offset:1024
	ds_read_b128 v[162:165], v166 offset:2048
	ds_read_b128 v[166:169], v166 offset:3072
	s_add_i32 m0, s17, 0xc000
	ds_read_b128 v[170:173], v187
	ds_read_b128 v[174:177], v187 offset:1024
	ds_read_b128 v[188:191], v187 offset:2048
	ds_read_b128 v[192:195], v187 offset:3072
	ds_read_b128 v[196:199], v187 offset:4096
	ds_read_b128 v[222:225], v187 offset:5120
	ds_read_b128 v[226:229], v187 offset:6144
	ds_read_b128 v[230:233], v187 offset:7168
	global_load_lds_dwordx4 v158, s[62:63]
	s_add_i32 m0, s17, 0xe000
	s_nop 0
	global_load_lds_dwordx4 v160, s[62:63]
	s_waitcnt vmcnt(8)
	s_waitcnt lgkmcnt(0)
	s_barrier
	s_setprio 1
	s_waitcnt lgkmcnt(0)
	v_mfma_f32_16x16x32_bf16 v[124:127], v[128:131], v[170:173], v[124:127]
	v_mfma_f32_16x16x32_bf16 v[116:119], v[136:139], v[170:173], v[116:119]
	v_mfma_f32_16x16x32_bf16 v[108:111], v[128:131], v[188:191], v[108:111]
	v_mfma_f32_16x16x32_bf16 v[100:103], v[136:139], v[188:191], v[100:103]
	v_mfma_f32_16x16x32_bf16 v[92:95], v[128:131], v[196:199], v[92:95]
	v_mfma_f32_16x16x32_bf16 v[84:87], v[136:139], v[196:199], v[84:87]
	v_mfma_f32_16x16x32_bf16 v[76:79], v[128:131], v[226:229], v[76:79]
	v_mfma_f32_16x16x32_bf16 v[68:71], v[136:139], v[226:229], v[68:71]
	v_mfma_f32_16x16x32_bf16 v[124:127], v[132:135], v[174:177], v[124:127]
	v_mfma_f32_16x16x32_bf16 v[116:119], v[140:143], v[174:177], v[116:119]
	v_mfma_f32_16x16x32_bf16 v[108:111], v[132:135], v[192:195], v[108:111]
	v_mfma_f32_16x16x32_bf16 v[100:103], v[140:143], v[192:195], v[100:103]
	v_mfma_f32_16x16x32_bf16 v[92:95], v[132:135], v[222:225], v[92:95]
	v_mfma_f32_16x16x32_bf16 v[84:87], v[140:143], v[222:225], v[84:87]
	v_mfma_f32_16x16x32_bf16 v[76:79], v[132:135], v[230:233], v[76:79]
	v_mfma_f32_16x16x32_bf16 v[68:71], v[140:143], v[230:233], v[68:71]
	s_setprio 0
	s_setprio 1
	v_mfma_f32_16x16x32_bf16 v[120:123], v[144:147], v[170:173], v[120:123]
	v_mfma_f32_16x16x32_bf16 v[112:115], v[162:165], v[170:173], v[112:115]
	v_mfma_f32_16x16x32_bf16 v[104:107], v[144:147], v[188:191], v[104:107]
	v_mfma_f32_16x16x32_bf16 v[96:99], v[162:165], v[188:191], v[96:99]
	v_mfma_f32_16x16x32_bf16 v[88:91], v[144:147], v[196:199], v[88:91]
	v_mfma_f32_16x16x32_bf16 v[80:83], v[162:165], v[196:199], v[80:83]
	v_mfma_f32_16x16x32_bf16 v[72:75], v[144:147], v[226:229], v[72:75]
	v_mfma_f32_16x16x32_bf16 v[64:67], v[162:165], v[226:229], v[64:67]
	v_mfma_f32_16x16x32_bf16 v[120:123], v[148:151], v[174:177], v[120:123]
	v_mfma_f32_16x16x32_bf16 v[112:115], v[166:169], v[174:177], v[112:115]
	v_mfma_f32_16x16x32_bf16 v[104:107], v[148:151], v[192:195], v[104:107]
	v_mfma_f32_16x16x32_bf16 v[96:99], v[166:169], v[192:195], v[96:99]
	v_mfma_f32_16x16x32_bf16 v[88:91], v[148:151], v[222:225], v[88:91]
	v_mfma_f32_16x16x32_bf16 v[80:83], v[166:169], v[222:225], v[80:83]
	v_mfma_f32_16x16x32_bf16 v[72:75], v[148:151], v[230:233], v[72:75]
	v_mfma_f32_16x16x32_bf16 v[64:67], v[166:169], v[230:233], v[64:67]
	s_setprio 0
	s_barrier
	s_add_i32 s25, s28, s15
	s_mov_b32 m0, s25
	ds_read_b128 v[170:173], v187 offset:16384
	ds_read_b128 v[174:177], v187 offset:17408
	ds_read_b128 v[188:191], v187 offset:18432
	ds_read_b128 v[192:195], v187 offset:19456
	ds_read_b128 v[196:199], v187 offset:20480
	ds_read_b128 v[222:225], v187 offset:21504
	ds_read_b128 v[226:229], v187 offset:22528
	ds_read_b128 v[230:233], v187 offset:23552
	global_load_lds_dwordx4 v200, s[64:65]
	s_add_i32 m0, s25, 0x2000
	s_add_u32 s78, s64, 0x40000
	s_addc_u32 s79, s65, 0
	s_add_i32 s24, s24, s15
	global_load_lds_dwordx4 v152, s[64:65]
	s_mov_b32 m0, s24
	s_nop 0
	global_load_lds_dwordx4 v200, s[78:79]
	s_add_i32 m0, s24, 0x2000
	s_nop 0
	global_load_lds_dwordx4 v152, s[78:79]
	s_mov_b32 m0, s17
	s_nop 0
	global_load_lds_dwordx4 v156, s[66:67]
	s_mov_b32 m0, s18
	s_nop 0
	global_load_lds_dwordx4 v154, s[66:67]
	s_waitcnt vmcnt(8)
	s_waitcnt lgkmcnt(0)
	s_barrier
	s_setprio 1
	s_waitcnt lgkmcnt(0)
	v_mfma_f32_16x16x32_bf16 v[60:63], v[128:131], v[170:173], v[60:63]
	v_mfma_f32_16x16x32_bf16 v[52:55], v[136:139], v[170:173], v[52:55]
	v_mfma_f32_16x16x32_bf16 v[44:47], v[128:131], v[188:191], v[44:47]
	v_mfma_f32_16x16x32_bf16 v[36:39], v[136:139], v[188:191], v[36:39]
	v_mfma_f32_16x16x32_bf16 v[28:31], v[128:131], v[196:199], v[28:31]
	v_mfma_f32_16x16x32_bf16 v[20:23], v[136:139], v[196:199], v[20:23]
	v_mfma_f32_16x16x32_bf16 v[12:15], v[128:131], v[226:229], v[12:15]
	v_mfma_f32_16x16x32_bf16 v[4:7], v[136:139], v[226:229], v[4:7]
	v_mfma_f32_16x16x32_bf16 v[60:63], v[132:135], v[174:177], v[60:63]
	v_mfma_f32_16x16x32_bf16 v[52:55], v[140:143], v[174:177], v[52:55]
	v_mfma_f32_16x16x32_bf16 v[44:47], v[132:135], v[192:195], v[44:47]
	v_mfma_f32_16x16x32_bf16 v[36:39], v[140:143], v[192:195], v[36:39]
	v_mfma_f32_16x16x32_bf16 v[28:31], v[132:135], v[222:225], v[28:31]
	v_mfma_f32_16x16x32_bf16 v[20:23], v[140:143], v[222:225], v[20:23]
	v_mfma_f32_16x16x32_bf16 v[12:15], v[132:135], v[230:233], v[12:15]
	v_mfma_f32_16x16x32_bf16 v[4:7], v[140:143], v[230:233], v[4:7]
	s_setprio 0
	s_setprio 1
	v_mfma_f32_16x16x32_bf16 v[56:59], v[144:147], v[170:173], v[56:59]
	v_mfma_f32_16x16x32_bf16 v[48:51], v[162:165], v[170:173], v[48:51]
	v_mfma_f32_16x16x32_bf16 v[40:43], v[144:147], v[188:191], v[40:43]
	v_mfma_f32_16x16x32_bf16 v[32:35], v[162:165], v[188:191], v[32:35]
	v_mfma_f32_16x16x32_bf16 v[24:27], v[144:147], v[196:199], v[24:27]
	v_mfma_f32_16x16x32_bf16 v[16:19], v[162:165], v[196:199], v[16:19]
	v_mfma_f32_16x16x32_bf16 v[8:11], v[144:147], v[226:229], v[8:11]
	v_mfma_f32_16x16x32_bf16 v[0:3], v[162:165], v[226:229], v[0:3]
	v_mfma_f32_16x16x32_bf16 v[56:59], v[148:151], v[174:177], v[56:59]
	v_mfma_f32_16x16x32_bf16 v[48:51], v[166:169], v[174:177], v[48:51]
	v_mfma_f32_16x16x32_bf16 v[40:43], v[148:151], v[192:195], v[40:43]
	v_mfma_f32_16x16x32_bf16 v[32:35], v[166:169], v[192:195], v[32:35]
	v_mfma_f32_16x16x32_bf16 v[24:27], v[148:151], v[222:225], v[24:27]
	v_mfma_f32_16x16x32_bf16 v[16:19], v[166:169], v[222:225], v[16:19]
	v_mfma_f32_16x16x32_bf16 v[8:11], v[148:151], v[230:233], v[8:11]
	v_mfma_f32_16x16x32_bf16 v[0:3], v[166:169], v[230:233], v[0:3]
	s_setprio 0
	s_barrier
; #define PG8_STAGE(bufoff, gbase, voff) do { _Pragma("unroll") for (int _i = 0; _i < 2; ++_i) \
;         __builtin_amdgcn_global_load_lds((const unsigned*)((const char*)(gbase) + (voff)[_i]), (LAS unsigned*)(lds + (bufoff) + ldsw + _i * 8192), 16, 0, 0); } while (0)
; #define PG8_LDA(dst, b, h) do { _Pragma("unroll") for (int m = 0; m < 4; ++m) _Pragma("unroll") for (int k = 0; k < 2; ++k) dst[m][k] = *(const LAS bf16x8*)(lds + PG8_SA(b, h) + aoff + m * 2048 + k * 1024); } while (0)
; #define PG8_LDB(dst, b, h) do { _Pragma("unroll") for (int n = 0; n < 2; ++n) _Pragma("unroll") for (int k = 0; k < 2; ++k) dst[n][k] = *(const LAS bf16x8*)(lds + PG8_SB(b, h) + boff + n * 2048 + k * 1024); } while (0)
; #define PG8_MMA(ai, bj, At, Bt) do { __builtin_amdgcn_s_setprio(1); _Pragma("unroll") for (int m = 0; m < 4; ++m) _Pragma("unroll") for (int n = 0; n < 2; ++n) _Pragma("unroll") for (int k = 0; k < 2; ++k) \
;         acc[ai][bj][m][n] = __builtin_amdgcn_mfma_f32_16x16x32_bf16(Bt[n][k], At[m][k], acc[ai][bj][m][n], 0, 0, 0); __builtin_amdgcn_s_setprio(0); } while (0)
; #define PG8_WAIT_V(n) asm volatile("s_waitcnt vmcnt(" #n ")" ::: "memory")
; #define PG8_WAIT_L(n) asm volatile("s_waitcnt lgkmcnt(" #n ")" ::: "memory")
; #define PG8_BAR __builtin_amdgcn_s_barrier()
; #define PG8_SCHED __builtin_amdgcn_sched_barrier(0)
; template <class Epi, class Addr>
; __device__ __forceinline__ void gemm_phase(LAS unsigned char* lds, const Gemm g, const StaticOrder& S, const Addr& AD, const Epi& E) {
;     ...
;             PG8_LDB(B0, 1, 0); PG8_LDB(B1, 1, 1); PG8_SCHED; PG8_LDA(At, 1, 0); PG8_STAGE(PG8_SA(0, 1), a2 + hstepA, voffA);
;             PG8_WAIT_V(8); PG8_WAIT_L(0); PG8_BAR; PG8_MMA(0, 0, At, B0); PG8_MMA(0, 1, At, B1); PG8_BAR; PG8_SCHED;
;             PG8_LDA(At, 1, 1); PG8_STAGE(PG8_SB(1, 0), b3, voffB); PG8_STAGE(PG8_SB(1, 1), b3 + hstepB, voffB); PG8_STAGE(PG8_SA(1, 0), a3, voffA);
;             PG8_WAIT_V(8); PG8_WAIT_L(0); PG8_BAR; PG8_MMA(1, 0, At, B0); PG8_MMA(1, 1, At, B1); PG8_BAR; PG8_SCHED;
;         }
	s_add_i32 s24, 0, 0x18000
	s_add_i32 s25, 0, 0x1c000
	v_add_u32_e32 v140, s24, v186
	v_add_u32_e32 v166, s25, v186
	ds_read_b128 v[128:131], v140
	ds_read_b128 v[132:135], v140 offset:1024
	ds_read_b128 v[136:139], v140 offset:2048
	ds_read_b128 v[140:143], v140 offset:3072
	ds_read_b128 v[144:147], v166
	ds_read_b128 v[148:151], v166 offset:1024
	ds_read_b128 v[162:165], v166 offset:2048
	ds_read_b128 v[166:169], v166 offset:3072
	s_add_u32 s66, s66, 0x40000
	s_addc_u32 s67, s67, 0
	s_mov_b32 m0, s19
	ds_read_b128 v[170:173], v187 offset:32768
	ds_read_b128 v[174:177], v187 offset:33792
	ds_read_b128 v[188:191], v187 offset:34816
	ds_read_b128 v[192:195], v187 offset:35840
	ds_read_b128 v[196:199], v187 offset:36864
	ds_read_b128 v[222:225], v187 offset:37888
	ds_read_b128 v[226:229], v187 offset:38912
	ds_read_b128 v[230:233], v187 offset:39936
	global_load_lds_dwordx4 v156, s[66:67]
	s_mov_b32 m0, s20
	s_nop 0
	global_load_lds_dwordx4 v154, s[66:67]
	s_waitcnt vmcnt(8)
	s_waitcnt lgkmcnt(0)
	s_barrier
	s_setprio 1
	s_waitcnt lgkmcnt(0)
	v_mfma_f32_16x16x32_bf16 v[124:127], v[128:131], v[170:173], v[124:127]
	v_mfma_f32_16x16x32_bf16 v[116:119], v[136:139], v[170:173], v[116:119]
	v_mfma_f32_16x16x32_bf16 v[108:111], v[128:131], v[188:191], v[108:111]
	v_mfma_f32_16x16x32_bf16 v[100:103], v[136:139], v[188:191], v[100:103]
	v_mfma_f32_16x16x32_bf16 v[92:95], v[128:131], v[196:199], v[92:95]
	v_mfma_f32_16x16x32_bf16 v[84:87], v[136:139], v[196:199], v[84:87]
	v_mfma_f32_16x16x32_bf16 v[76:79], v[128:131], v[226:229], v[76:79]
	v_mfma_f32_16x16x32_bf16 v[68:71], v[136:139], v[226:229], v[68:71]
	v_mfma_f32_16x16x32_bf16 v[124:127], v[132:135], v[174:177], v[124:127]
	v_mfma_f32_16x16x32_bf16 v[116:119], v[140:143], v[174:177], v[116:119]
	v_mfma_f32_16x16x32_bf16 v[108:111], v[132:135], v[192:195], v[108:111]
	v_mfma_f32_16x16x32_bf16 v[100:103], v[140:143], v[192:195], v[100:103]
	v_mfma_f32_16x16x32_bf16 v[92:95], v[132:135], v[222:225], v[92:95]
	v_mfma_f32_16x16x32_bf16 v[84:87], v[140:143], v[222:225], v[84:87]
	v_mfma_f32_16x16x32_bf16 v[76:79], v[132:135], v[230:233], v[76:79]
	v_mfma_f32_16x16x32_bf16 v[68:71], v[140:143], v[230:233], v[68:71]
	s_setprio 0
	s_setprio 1
	v_mfma_f32_16x16x32_bf16 v[120:123], v[144:147], v[170:173], v[120:123]
	v_mfma_f32_16x16x32_bf16 v[112:115], v[162:165], v[170:173], v[112:115]
	v_mfma_f32_16x16x32_bf16 v[104:107], v[144:147], v[188:191], v[104:107]
	v_mfma_f32_16x16x32_bf16 v[96:99], v[162:165], v[188:191], v[96:99]
	v_mfma_f32_16x16x32_bf16 v[88:91], v[144:147], v[196:199], v[88:91]
	v_mfma_f32_16x16x32_bf16 v[80:83], v[162:165], v[196:199], v[80:83]
	v_mfma_f32_16x16x32_bf16 v[72:75], v[144:147], v[226:229], v[72:75]
	v_mfma_f32_16x16x32_bf16 v[64:67], v[162:165], v[226:229], v[64:67]
	v_mfma_f32_16x16x32_bf16 v[120:123], v[148:151], v[174:177], v[120:123]
	v_mfma_f32_16x16x32_bf16 v[112:115], v[166:169], v[174:177], v[112:115]
	v_mfma_f32_16x16x32_bf16 v[104:107], v[148:151], v[192:195], v[104:107]
	v_mfma_f32_16x16x32_bf16 v[96:99], v[166:169], v[192:195], v[96:99]
	v_mfma_f32_16x16x32_bf16 v[88:91], v[148:151], v[222:225], v[88:91]
	v_mfma_f32_16x16x32_bf16 v[80:83], v[166:169], v[222:225], v[80:83]
	v_mfma_f32_16x16x32_bf16 v[72:75], v[148:151], v[230:233], v[72:75]
	v_mfma_f32_16x16x32_bf16 v[64:67], v[166:169], v[230:233], v[64:67]
	s_setprio 0
	s_barrier
	s_add_i32 s24, s24, s15
	s_add_u32 s78, s64, s42
	s_addc_u32 s79, s65, s43
	s_mov_b32 m0, s24
	ds_read_b128 v[170:173], v187 offset:49152
	ds_read_b128 v[174:177], v187 offset:50176
	ds_read_b128 v[188:191], v187 offset:51200
	ds_read_b128 v[192:195], v187 offset:52224
	ds_read_b128 v[196:199], v187 offset:53248
	ds_read_b128 v[222:225], v187 offset:54272
	ds_read_b128 v[226:229], v187 offset:55296
	ds_read_b128 v[230:233], v187 offset:56320
	global_load_lds_dwordx4 v200, s[78:79]
	s_add_i32 m0, s24, 0x2000
	s_add_u32 s64, s64, 0x40080
	s_addc_u32 s65, s65, 0
	s_add_i32 s24, s25, s15
	global_load_lds_dwordx4 v152, s[78:79]
	s_mov_b32 m0, s24
	s_add_u32 s78, s66, s42
	s_addc_u32 s79, s67, s43
	global_load_lds_dwordx4 v200, s[64:65]
	s_add_i32 m0, s24, 0x2000
	s_sub_u32 s78, s78, 0x40000
	s_subb_u32 s79, s79, 0
	global_load_lds_dwordx4 v152, s[64:65]
	s_mov_b32 m0, s68
	s_nop 0
	global_load_lds_dwordx4 v156, s[78:79]
	s_mov_b32 m0, s69
	s_nop 0
	global_load_lds_dwordx4 v154, s[78:79]
	s_waitcnt vmcnt(8)
	s_waitcnt lgkmcnt(0)
	s_barrier
	s_setprio 1
	s_waitcnt lgkmcnt(0)
	v_mfma_f32_16x16x32_bf16 v[60:63], v[128:131], v[170:173], v[60:63]
	v_mfma_f32_16x16x32_bf16 v[52:55], v[136:139], v[170:173], v[52:55]
	v_mfma_f32_16x16x32_bf16 v[44:47], v[128:131], v[188:191], v[44:47]
	v_mfma_f32_16x16x32_bf16 v[36:39], v[136:139], v[188:191], v[36:39]
	v_mfma_f32_16x16x32_bf16 v[28:31], v[128:131], v[196:199], v[28:31]
	v_mfma_f32_16x16x32_bf16 v[20:23], v[136:139], v[196:199], v[20:23]
	v_mfma_f32_16x16x32_bf16 v[12:15], v[128:131], v[226:229], v[12:15]
	v_mfma_f32_16x16x32_bf16 v[4:7], v[136:139], v[226:229], v[4:7]
	v_mfma_f32_16x16x32_bf16 v[60:63], v[132:135], v[174:177], v[60:63]
	v_mfma_f32_16x16x32_bf16 v[52:55], v[140:143], v[174:177], v[52:55]
	v_mfma_f32_16x16x32_bf16 v[44:47], v[132:135], v[192:195], v[44:47]
	v_mfma_f32_16x16x32_bf16 v[36:39], v[140:143], v[192:195], v[36:39]
	v_mfma_f32_16x16x32_bf16 v[28:31], v[132:135], v[222:225], v[28:31]
	v_mfma_f32_16x16x32_bf16 v[20:23], v[140:143], v[222:225], v[20:23]
	v_mfma_f32_16x16x32_bf16 v[12:15], v[132:135], v[230:233], v[12:15]
	v_mfma_f32_16x16x32_bf16 v[4:7], v[140:143], v[230:233], v[4:7]
	s_setprio 0
	s_setprio 1
	v_mfma_f32_16x16x32_bf16 v[56:59], v[144:147], v[170:173], v[56:59]
	v_mfma_f32_16x16x32_bf16 v[48:51], v[162:165], v[170:173], v[48:51]
	v_mfma_f32_16x16x32_bf16 v[40:43], v[144:147], v[188:191], v[40:43]
	v_mfma_f32_16x16x32_bf16 v[32:35], v[162:165], v[188:191], v[32:35]
	v_mfma_f32_16x16x32_bf16 v[24:27], v[144:147], v[196:199], v[24:27]
	v_mfma_f32_16x16x32_bf16 v[16:19], v[162:165], v[196:199], v[16:19]
	v_mfma_f32_16x16x32_bf16 v[8:11], v[144:147], v[226:229], v[8:11]
	v_mfma_f32_16x16x32_bf16 v[0:3], v[162:165], v[226:229], v[0:3]
	v_mfma_f32_16x16x32_bf16 v[56:59], v[148:151], v[174:177], v[56:59]
	v_mfma_f32_16x16x32_bf16 v[48:51], v[166:169], v[174:177], v[48:51]
	v_mfma_f32_16x16x32_bf16 v[40:43], v[148:151], v[192:195], v[40:43]
	v_mfma_f32_16x16x32_bf16 v[32:35], v[166:169], v[192:195], v[32:35]
	v_mfma_f32_16x16x32_bf16 v[24:27], v[148:151], v[222:225], v[24:27]
	v_mfma_f32_16x16x32_bf16 v[16:19], v[166:169], v[222:225], v[16:19]
	v_mfma_f32_16x16x32_bf16 v[8:11], v[148:151], v[230:233], v[8:11]
	v_mfma_f32_16x16x32_bf16 v[0:3], v[166:169], v[230:233], v[0:3]
	s_setprio 0
	s_barrier
	s_add_u32 s62, s62, 0x100
	s_addc_u32 s63, s63, 0
	s_add_u32 s74, s74, 0x100
	s_addc_u32 s75, s75, 0
	s_cmp_ge_i32 s76, s21
	s_mov_b32 s64, s76
	s_cbranch_scc0 .LBB0_1256
